# v11 + FFN1 meta-row skinny GEMM: row-contiguous (full 128-B line) weight loads, per-wave LDS transpose to MFMA fragments
# baseline (speedup 1.0000x reference)
.LBB0_118:
	s_or_b64 exec, exec, s[2:3]
	s_mov_b64 s[2:3], s[90:91]
	s_cmpk_gt_i32 s22, 0x2af
	s_barrier
	v_mbcnt_lo_u32_b32 v1, -1, 0
	v_mbcnt_hi_u32_b32 v1, -1, v1
	s_cbranch_scc1 .LBB0_123
	s_load_dwordx2 s[4:5], s[2:3], 0xc8
	v_and_b32_e32 v2, 15, v1
	v_and_b32_e32 v0, -16, v1
	v_lshlrev_b32_e32 v3, 13, v2
	v_or_b32_e32 v68, 0x4000, v2
	s_waitcnt lgkmcnt(0)
	s_add_u32 s8, s4, 0x800000
	s_addc_u32 s9, s5, 0
	s_lshl_b32 s0, s81, 10
	s_lshl_b32 s10, s81, 11
	s_cmp_lt_u32 s61, 64
	v_lshl_add_u32 v70, v1, 4, 0
	v_add3_u32 v0, v0, s0, v3
	s_cselect_b64 s[2:3], -1, 0
	v_ashrrev_i32_e32 v1, 2, v1
	v_lshlrev_b32_e32 v2, 13, v68
	v_mov_b32_e32 v3, 0
	s_add_u32 s6, s4, 0x27600000
	v_and_b32_e32 v71, -4, v1
	v_mov_b32_e32 v1, v3
	s_waitcnt vmcnt(4)
	v_add_u32_e32 v4, 64, v0
	v_mov_b32_e32 v5, v3
	v_add_u32_e32 v6, 0x80, v0
	v_mov_b32_e32 v7, v3
	v_add_u32_e32 v8, 0xc0, v0
	v_mov_b32_e32 v9, v3
	v_add_u32_e32 v10, 0x100, v0
	v_mov_b32_e32 v11, v3
	v_add_u32_e32 v12, 0x140, v0
	v_mov_b32_e32 v13, v3
	v_add_u32_e32 v14, 0x180, v0
	v_mov_b32_e32 v15, v3
	v_add_u32_e32 v16, 0x1c0, v0
	v_mov_b32_e32 v17, v3
	v_add_u32_e32 v18, 0x200, v0
	v_mov_b32_e32 v19, v3
	v_add_u32_e32 v20, 0x240, v0
	v_mov_b32_e32 v21, v3
	v_add_u32_e32 v22, 0x280, v0
	v_mov_b32_e32 v23, v3
	v_add_u32_e32 v24, 0x2c0, v0
	v_mov_b32_e32 v25, v3
	v_add_u32_e32 v26, 0x300, v0
	v_mov_b32_e32 v27, v3
	v_add_u32_e32 v28, 0x340, v0
	v_mov_b32_e32 v29, v3
	v_add_u32_e32 v30, 0x380, v0
	v_mov_b32_e32 v31, v3
	v_add_u32_e32 v32, 0x3c0, v0
	v_mov_b32_e32 v33, v3
	s_addc_u32 s7, s5, 0
	v_lshl_add_u64 v[66:67], s[4:5], 0, v[2:3]
	v_lshlrev_b32_e32 v2, 2, v68
	v_lshl_add_u64 v[34:35], s[6:7], 0, v[0:1]
	v_lshl_add_u64 v[36:37], s[6:7], 0, v[4:5]
	v_lshl_add_u64 v[38:39], s[6:7], 0, v[6:7]
	v_lshl_add_u64 v[40:41], s[6:7], 0, v[8:9]
	v_lshl_add_u64 v[42:43], s[6:7], 0, v[10:11]
	v_lshl_add_u64 v[44:45], s[6:7], 0, v[12:13]
	v_lshl_add_u64 v[46:47], s[6:7], 0, v[14:15]
	v_lshl_add_u64 v[48:49], s[6:7], 0, v[16:17]
	v_lshl_add_u64 v[50:51], s[6:7], 0, v[18:19]
	v_lshl_add_u64 v[52:53], s[6:7], 0, v[20:21]
	v_lshl_add_u64 v[54:55], s[6:7], 0, v[22:23]
	v_lshl_add_u64 v[56:57], s[6:7], 0, v[24:25]
	v_lshl_add_u64 v[58:59], s[6:7], 0, v[26:27]
	v_lshl_add_u64 v[60:61], s[6:7], 0, v[28:29]
	v_lshl_add_u64 v[62:63], s[6:7], 0, v[30:31]
	v_lshl_add_u64 v[64:65], s[6:7], 0, v[32:33]
	s_mov_b64 s[6:7], 0x2fa00000
	v_lshl_add_u64 v[68:69], s[4:5], 0, v[2:3]
	s_mov_b64 s[4:5], 0x600000
	v_lshl_add_u64 v[66:67], v[66:67], 0, s[6:7]
	v_lshl_add_u64 v[68:69], v[68:69], 0, s[4:5]
	s_lshl_b32 s11, s22, 4
	s_lshl_b32 s12, s72, 4
	s_lshl_b32 s13, s22, 5
	s_lshl_b32 s14, s72, 5
	s_movk_i32 s15, 0x7fff
	s_mov_b32 s16, 0x8200000
	v_mov_b32_e32 v72, 1
	s_mov_b32 s17, s22
	global_load_dwordx4 v[4:7], v[34:35], off
	global_load_dwordx4 v[8:11], v[34:35], off offset:64
	global_load_dwordx4 v[12:15], v[34:35], off offset:128
	global_load_dwordx4 v[16:19], v[34:35], off offset:192
	global_load_dwordx4 v[20:23], v[34:35], off offset:256
	global_load_dwordx4 v[24:27], v[34:35], off offset:320
	global_load_dwordx4 v[28:31], v[34:35], off offset:384
	global_load_dwordx4 v[36:39], v[34:35], off offset:448
	global_load_dwordx4 v[40:43], v[34:35], off offset:512
	global_load_dwordx4 v[44:47], v[34:35], off offset:576
	global_load_dwordx4 v[48:51], v[34:35], off offset:640
	global_load_dwordx4 v[52:55], v[34:35], off offset:704
	global_load_dwordx4 v[56:59], v[34:35], off offset:768
	global_load_dwordx4 v[60:63], v[34:35], off offset:832
	global_load_dwordx4 v[246:249], v[34:35], off offset:896
	global_load_dwordx4 v[250:253], v[34:35], off offset:960
	v_mbcnt_lo_u32_b32 v2, -1, 0
	v_mbcnt_hi_u32_b32 v2, -1, v2
	v_lshrrev_b32_e32 v34, 5, v2
	v_and_b32_e32 v35, 31, v2
	v_lshlrev_b32_e32 v32, 13, v34
	v_lshl_add_u32 v32, v35, 4, v32
	s_lshl_b32 s0, s81, 10
	v_add_u32_e32 v32, s0, v32
	v_add_u32_e32 v33, 0x4000, v32
	v_add_u32_e32 v64, 0x8000, v32
	v_add_u32_e32 v65, 0xc000, v32
	v_add_u32_e32 v242, 0x10000, v32
	v_add_u32_e32 v243, 0x14000, v32
	v_add_u32_e32 v244, 0x18000, v32
	v_add_u32_e32 v245, 0x1c000, v32
	s_mul_i32 s0, s81, 0x2100
	s_add_i32 s0, s0, 0x4000
	v_mul_u32_u24_e32 v34, 0x210, v34
	v_lshl_add_u32 v34, v35, 4, v34
	v_add_u32_e32 v34, s0, v34
	v_and_b32_e32 v35, 15, v2
	v_mul_u32_u24_e32 v35, 0x210, v35
	v_lshrrev_b32_e32 v2, 4, v2
	v_lshl_add_u32 v35, v2, 4, v35
	v_add_u32_e32 v35, s0, v35
	s_branch .LBB0_121

.LBB0_121:
	s_and_b32 s0, s13, 0xffffff00
	s_and_b32 s1, s11, 0x70
	s_or_b32 s4, s0, s1
	s_ashr_i32 s5, s4, 31
	s_lshl_b64 s[4:5], s[4:5], 13
	s_add_u32 s4, s8, s4
	s_addc_u32 s5, s9, s5
	s_add_u32 s6, s4, 0x100000
	s_addc_u32 s7, s5, 0
	v_add_u32_e32 v2, s10, v70
	s_andn2_b64 vcc, exec, s[2:3]
	global_load_dwordx4 v[82:85], v32, s[4:5]
	global_load_dwordx4 v[86:89], v33, s[4:5]
	global_load_dwordx4 v[90:93], v64, s[4:5]
	global_load_dwordx4 v[94:97], v65, s[4:5]
	global_load_dwordx4 v[98:101], v242, s[4:5]
	global_load_dwordx4 v[102:105], v243, s[4:5]
	global_load_dwordx4 v[106:109], v244, s[4:5]
	global_load_dwordx4 v[110:113], v245, s[4:5]
	global_load_dwordx4 v[114:117], v32, s[4:5] offset:512
	global_load_dwordx4 v[118:121], v33, s[4:5] offset:512
	global_load_dwordx4 v[122:125], v64, s[4:5] offset:512
	global_load_dwordx4 v[126:129], v65, s[4:5] offset:512
	global_load_dwordx4 v[130:133], v242, s[4:5] offset:512
	global_load_dwordx4 v[134:137], v243, s[4:5] offset:512
	global_load_dwordx4 v[138:141], v244, s[4:5] offset:512
	global_load_dwordx4 v[142:145], v245, s[4:5] offset:512
	global_load_dwordx4 v[146:149], v32, s[6:7]
	global_load_dwordx4 v[150:153], v33, s[6:7]
	global_load_dwordx4 v[154:157], v64, s[6:7]
	global_load_dwordx4 v[158:161], v65, s[6:7]
	global_load_dwordx4 v[162:165], v242, s[6:7]
	global_load_dwordx4 v[166:169], v243, s[6:7]
	global_load_dwordx4 v[170:173], v244, s[6:7]
	global_load_dwordx4 v[174:177], v245, s[6:7]
	global_load_dwordx4 v[178:181], v32, s[6:7] offset:512
	global_load_dwordx4 v[182:185], v33, s[6:7] offset:512
	global_load_dwordx4 v[186:189], v64, s[6:7] offset:512
	global_load_dwordx4 v[190:193], v65, s[6:7] offset:512
	global_load_dwordx4 v[194:197], v242, s[6:7] offset:512
	global_load_dwordx4 v[198:201], v243, s[6:7] offset:512
	global_load_dwordx4 v[202:205], v244, s[6:7] offset:512
	global_load_dwordx4 v[206:209], v245, s[6:7] offset:512
	s_waitcnt vmcnt(31)
	ds_write_b128 v34, v[82:85]
	s_waitcnt vmcnt(30)
	ds_write_b128 v34, v[86:89] offset:1056
	s_waitcnt vmcnt(29)
	ds_write_b128 v34, v[90:93] offset:2112
	s_waitcnt vmcnt(28)
	ds_write_b128 v34, v[94:97] offset:3168
	s_waitcnt vmcnt(27)
	ds_write_b128 v34, v[98:101] offset:4224
	s_waitcnt vmcnt(26)
	ds_write_b128 v34, v[102:105] offset:5280
	s_waitcnt vmcnt(25)
	ds_write_b128 v34, v[106:109] offset:6336
	s_waitcnt vmcnt(24)
	ds_write_b128 v34, v[110:113] offset:7392
	s_waitcnt lgkmcnt(0)
	ds_read_b128 v[210:213], v35
	ds_read_b128 v[214:217], v35 offset:64
	ds_read_b128 v[218:221], v35 offset:128
	ds_read_b128 v[222:225], v35 offset:192
	ds_read_b128 v[226:229], v35 offset:256
	ds_read_b128 v[230:233], v35 offset:320
	ds_read_b128 v[234:237], v35 offset:384
	ds_read_b128 v[238:241], v35 offset:448
	s_waitcnt lgkmcnt(7)
	v_mfma_f32_16x16x32_bf16 v[74:77], v[210:213], v[4:7], 0
	s_waitcnt lgkmcnt(6)
	v_mfma_f32_16x16x32_bf16 v[74:77], v[214:217], v[8:11], v[74:77]
	s_waitcnt lgkmcnt(5)
	v_mfma_f32_16x16x32_bf16 v[74:77], v[218:221], v[12:15], v[74:77]
	s_waitcnt lgkmcnt(4)
	v_mfma_f32_16x16x32_bf16 v[74:77], v[222:225], v[16:19], v[74:77]
	s_waitcnt lgkmcnt(3)
	v_mfma_f32_16x16x32_bf16 v[74:77], v[226:229], v[20:23], v[74:77]
	s_waitcnt lgkmcnt(2)
	v_mfma_f32_16x16x32_bf16 v[74:77], v[230:233], v[24:27], v[74:77]
	s_waitcnt lgkmcnt(1)
	v_mfma_f32_16x16x32_bf16 v[74:77], v[234:237], v[28:31], v[74:77]
	s_waitcnt lgkmcnt(0)
	v_mfma_f32_16x16x32_bf16 v[74:77], v[238:241], v[36:39], v[74:77]
	s_waitcnt vmcnt(23)
	ds_write_b128 v34, v[114:117]
	s_waitcnt vmcnt(22)
	ds_write_b128 v34, v[118:121] offset:1056
	s_waitcnt vmcnt(21)
	ds_write_b128 v34, v[122:125] offset:2112
	s_waitcnt vmcnt(20)
	ds_write_b128 v34, v[126:129] offset:3168
	s_waitcnt vmcnt(19)
	ds_write_b128 v34, v[130:133] offset:4224
	s_waitcnt vmcnt(18)
	ds_write_b128 v34, v[134:137] offset:5280
	s_waitcnt vmcnt(17)
	ds_write_b128 v34, v[138:141] offset:6336
	s_waitcnt vmcnt(16)
	ds_write_b128 v34, v[142:145] offset:7392
	s_waitcnt lgkmcnt(0)
	ds_read_b128 v[210:213], v35
	ds_read_b128 v[214:217], v35 offset:64
	ds_read_b128 v[218:221], v35 offset:128
	ds_read_b128 v[222:225], v35 offset:192
	ds_read_b128 v[226:229], v35 offset:256
	ds_read_b128 v[230:233], v35 offset:320
	ds_read_b128 v[234:237], v35 offset:384
	ds_read_b128 v[238:241], v35 offset:448
	s_waitcnt lgkmcnt(7)
	v_mfma_f32_16x16x32_bf16 v[74:77], v[210:213], v[40:43], v[74:77]
	s_waitcnt lgkmcnt(6)
	v_mfma_f32_16x16x32_bf16 v[74:77], v[214:217], v[44:47], v[74:77]
	s_waitcnt lgkmcnt(5)
	v_mfma_f32_16x16x32_bf16 v[74:77], v[218:221], v[48:51], v[74:77]
	s_waitcnt lgkmcnt(4)
	v_mfma_f32_16x16x32_bf16 v[74:77], v[222:225], v[52:55], v[74:77]
	s_waitcnt lgkmcnt(3)
	v_mfma_f32_16x16x32_bf16 v[74:77], v[226:229], v[56:59], v[74:77]
	s_waitcnt lgkmcnt(2)
	v_mfma_f32_16x16x32_bf16 v[74:77], v[230:233], v[60:63], v[74:77]
	s_waitcnt lgkmcnt(1)
	v_mfma_f32_16x16x32_bf16 v[74:77], v[234:237], v[246:249], v[74:77]
	s_waitcnt lgkmcnt(0)
	v_mfma_f32_16x16x32_bf16 v[74:77], v[238:241], v[250:253], v[74:77]
	s_waitcnt vmcnt(15)
	ds_write_b128 v34, v[146:149]
	s_waitcnt vmcnt(14)
	ds_write_b128 v34, v[150:153] offset:1056
	s_waitcnt vmcnt(13)
	ds_write_b128 v34, v[154:157] offset:2112
	s_waitcnt vmcnt(12)
	ds_write_b128 v34, v[158:161] offset:3168
	s_waitcnt vmcnt(11)
	ds_write_b128 v34, v[162:165] offset:4224
	s_waitcnt vmcnt(10)
	ds_write_b128 v34, v[166:169] offset:5280
	s_waitcnt vmcnt(9)
	ds_write_b128 v34, v[170:173] offset:6336
	s_waitcnt vmcnt(8)
	ds_write_b128 v34, v[174:177] offset:7392
	s_waitcnt lgkmcnt(0)
	ds_read_b128 v[210:213], v35
	ds_read_b128 v[214:217], v35 offset:64
	ds_read_b128 v[218:221], v35 offset:128
	ds_read_b128 v[222:225], v35 offset:192
	ds_read_b128 v[226:229], v35 offset:256
	ds_read_b128 v[230:233], v35 offset:320
	ds_read_b128 v[234:237], v35 offset:384
	ds_read_b128 v[238:241], v35 offset:448
	s_waitcnt lgkmcnt(7)
	v_mfma_f32_16x16x32_bf16 v[78:81], v[210:213], v[4:7], 0
	s_waitcnt lgkmcnt(6)
	v_mfma_f32_16x16x32_bf16 v[78:81], v[214:217], v[8:11], v[78:81]
	s_waitcnt lgkmcnt(5)
	v_mfma_f32_16x16x32_bf16 v[78:81], v[218:221], v[12:15], v[78:81]
	s_waitcnt lgkmcnt(4)
	v_mfma_f32_16x16x32_bf16 v[78:81], v[222:225], v[16:19], v[78:81]
	s_waitcnt lgkmcnt(3)
	v_mfma_f32_16x16x32_bf16 v[78:81], v[226:229], v[20:23], v[78:81]
	s_waitcnt lgkmcnt(2)
	v_mfma_f32_16x16x32_bf16 v[78:81], v[230:233], v[24:27], v[78:81]
	s_waitcnt lgkmcnt(1)
	v_mfma_f32_16x16x32_bf16 v[78:81], v[234:237], v[28:31], v[78:81]
	s_waitcnt lgkmcnt(0)
	v_mfma_f32_16x16x32_bf16 v[78:81], v[238:241], v[36:39], v[78:81]
	s_waitcnt vmcnt(7)
	ds_write_b128 v34, v[178:181]
	s_waitcnt vmcnt(6)
	ds_write_b128 v34, v[182:185] offset:1056
	s_waitcnt vmcnt(5)
	ds_write_b128 v34, v[186:189] offset:2112
	s_waitcnt vmcnt(4)
	ds_write_b128 v34, v[190:193] offset:3168
	s_waitcnt vmcnt(3)
	ds_write_b128 v34, v[194:197] offset:4224
	s_waitcnt vmcnt(2)
	ds_write_b128 v34, v[198:201] offset:5280
	s_waitcnt vmcnt(1)
	ds_write_b128 v34, v[202:205] offset:6336
	s_waitcnt vmcnt(0)
	ds_write_b128 v34, v[206:209] offset:7392
	s_waitcnt lgkmcnt(0)
	ds_read_b128 v[210:213], v35
	ds_read_b128 v[214:217], v35 offset:64
	ds_read_b128 v[218:221], v35 offset:128
	ds_read_b128 v[222:225], v35 offset:192
	ds_read_b128 v[226:229], v35 offset:256
	ds_read_b128 v[230:233], v35 offset:320
	ds_read_b128 v[234:237], v35 offset:384
	ds_read_b128 v[238:241], v35 offset:448
	s_waitcnt lgkmcnt(7)
	v_mfma_f32_16x16x32_bf16 v[78:81], v[210:213], v[40:43], v[78:81]
	s_waitcnt lgkmcnt(6)
	v_mfma_f32_16x16x32_bf16 v[78:81], v[214:217], v[44:47], v[78:81]
	s_waitcnt lgkmcnt(5)
	v_mfma_f32_16x16x32_bf16 v[78:81], v[218:221], v[48:51], v[78:81]
	s_waitcnt lgkmcnt(4)
	v_mfma_f32_16x16x32_bf16 v[78:81], v[222:225], v[52:55], v[78:81]
	s_waitcnt lgkmcnt(3)
	v_mfma_f32_16x16x32_bf16 v[78:81], v[226:229], v[56:59], v[78:81]
	s_waitcnt lgkmcnt(2)
	v_mfma_f32_16x16x32_bf16 v[78:81], v[230:233], v[60:63], v[78:81]
	s_waitcnt lgkmcnt(1)
	v_mfma_f32_16x16x32_bf16 v[78:81], v[234:237], v[246:249], v[78:81]
	s_waitcnt lgkmcnt(0)
	v_mfma_f32_16x16x32_bf16 v[78:81], v[238:241], v[250:253], v[78:81]
	s_nop 7
	ds_write_b128 v2, v[74:77]
	s_nop 0
	ds_write_b128 v2, v[78:81] offset:1024
	s_waitcnt lgkmcnt(0)
	s_waitcnt lgkmcnt(0)
	s_barrier
	s_cbranch_vccnz .LBB0_120
	global_load_dword v138, v[68:69], off
	ds_read_b128 v[74:77], v70
	ds_read_b128 v[78:81], v70 offset:1024
	ds_read_b128 v[82:85], v70 offset:2048
	ds_read_b128 v[86:89], v70 offset:3072
	ds_read_b128 v[90:93], v70 offset:4096
	ds_read_b128 v[94:97], v70 offset:5120
	ds_read_b128 v[98:101], v70 offset:6144
	ds_read_b128 v[102:105], v70 offset:7168
	ds_read_b128 v[106:109], v70 offset:8192
	ds_read_b128 v[110:113], v70 offset:9216
	ds_read_b128 v[114:117], v70 offset:10240
	ds_read_b128 v[118:121], v70 offset:11264
	ds_read_b128 v[122:125], v70 offset:12288
	ds_read_b128 v[126:129], v70 offset:13312
	ds_read_b128 v[130:133], v70 offset:14336
	ds_read_b128 v[134:137], v70 offset:15360
	s_waitcnt lgkmcnt(13)
	v_pk_add_f32 v[76:77], v[76:77], v[84:85]
	v_pk_add_f32 v[74:75], v[74:75], v[82:83]
	s_waitcnt lgkmcnt(12)
	v_pk_add_f32 v[78:79], v[78:79], v[86:87]
	s_waitcnt lgkmcnt(11)
	v_pk_add_f32 v[76:77], v[76:77], v[92:93]
	v_pk_add_f32 v[74:75], v[74:75], v[90:91]
	s_waitcnt lgkmcnt(10)
	v_pk_add_f32 v[78:79], v[78:79], v[94:95]
	s_waitcnt lgkmcnt(9)
	v_pk_add_f32 v[76:77], v[76:77], v[100:101]
	v_pk_add_f32 v[74:75], v[74:75], v[98:99]
	s_waitcnt lgkmcnt(8)
	v_pk_add_f32 v[78:79], v[78:79], v[102:103]
	s_waitcnt lgkmcnt(7)
	v_pk_add_f32 v[76:77], v[76:77], v[108:109]
	v_pk_add_f32 v[74:75], v[74:75], v[106:107]
	s_waitcnt lgkmcnt(6)
	v_pk_add_f32 v[78:79], v[78:79], v[110:111]
	s_waitcnt lgkmcnt(5)
	v_pk_add_f32 v[76:77], v[76:77], v[116:117]
	v_pk_add_f32 v[74:75], v[74:75], v[114:115]
	s_waitcnt lgkmcnt(4)
	v_pk_add_f32 v[78:79], v[78:79], v[118:119]
	s_waitcnt lgkmcnt(3)
	v_pk_add_f32 v[76:77], v[76:77], v[124:125]
	v_pk_add_f32 v[74:75], v[74:75], v[122:123]
	v_add_u32_e32 v2, s11, v71
	s_waitcnt lgkmcnt(2)
	v_pk_add_f32 v[78:79], v[78:79], v[126:127]
	s_waitcnt lgkmcnt(1)
	v_pk_add_f32 v[76:77], v[76:77], v[132:133]
	v_pk_add_f32 v[74:75], v[74:75], v[130:131]
	v_ashrrev_i32_e32 v73, 12, v2
	s_waitcnt lgkmcnt(0)
	v_pk_add_f32 v[78:79], v[78:79], v[134:135]
	v_mad_i64_i32 v[140:141], s[4:5], v73, s16, v[66:67]
	v_pk_add_f32 v[80:81], v[80:81], v[88:89]
	v_and_b32_e32 v2, 0xffc, v2
	v_pk_add_f32 v[80:81], v[80:81], v[96:97]
	v_lshlrev_b32_e32 v2, 1, v2
	v_pk_add_f32 v[80:81], v[80:81], v[104:105]
	s_waitcnt vmcnt(0)
	v_pk_mul_f32 v[76:77], v[76:77], v[138:139] op_sel_hi:[1,0]
	v_pk_mul_f32 v[74:75], v[74:75], v[138:139] op_sel_hi:[1,0]
	v_pk_mul_f32 v[78:79], v[78:79], v[138:139] op_sel_hi:[1,0]
	v_mul_f32_e32 v73, 0xbfb8aa3b, v74
	v_mul_f32_e32 v86, 0xbfb8aa3b, v75
	v_mul_f32_e32 v87, 0xbfb8aa3b, v76
	v_mul_f32_e32 v88, 0xbfb8aa3b, v77
	v_mov_b32_e32 v82, v74
	v_mov_b32_e32 v83, v76
	v_mov_b32_e32 v84, v78
	v_exp_f32_e32 v73, v73
	v_exp_f32_e32 v74, v86
	v_exp_f32_e32 v76, v87
	v_exp_f32_e32 v78, v88
	v_pk_add_f32 v[80:81], v[80:81], v[112:113]
	v_add_f32_e32 v73, 1.0, v73
	v_add_f32_e32 v74, 1.0, v74
	v_add_f32_e32 v76, 1.0, v76
	v_add_f32_e32 v78, 1.0, v78
	v_pk_add_f32 v[80:81], v[80:81], v[120:121]
	v_rcp_f32_e32 v86, v73
	v_rcp_f32_e32 v88, v74
	v_rcp_f32_e32 v87, v76
	v_rcp_f32_e32 v89, v78
	v_pk_add_f32 v[80:81], v[80:81], v[128:129]
	v_mov_b32_e32 v76, v75
	v_pk_add_f32 v[80:81], v[80:81], v[136:137]
	v_pk_mul_f32 v[74:75], v[82:83], v[86:87]
	v_pk_mul_f32 v[80:81], v[80:81], v[138:139] op_sel_hi:[1,0]
	v_pk_mul_f32 v[76:77], v[76:77], v[88:89]
	v_mov_b32_e32 v85, v80
	v_mov_b32_e32 v80, v79
	v_pk_mul_f32 v[74:75], v[84:85], v[74:75]
	v_pk_mul_f32 v[76:77], v[80:81], v[76:77]
	v_and_b32_sdwa v73, v75, v72 dst_sel:DWORD dst_unused:UNUSED_PAD src0_sel:WORD_1 src1_sel:DWORD
	v_and_b32_sdwa v79, v77, v72 dst_sel:DWORD dst_unused:UNUSED_PAD src0_sel:WORD_1 src1_sel:DWORD
	v_and_b32_sdwa v80, v76, v72 dst_sel:DWORD dst_unused:UNUSED_PAD src0_sel:WORD_1 src1_sel:DWORD
	v_and_b32_sdwa v78, v74, v72 dst_sel:DWORD dst_unused:UNUSED_PAD src0_sel:WORD_1 src1_sel:DWORD
	v_add3_u32 v73, v75, v73, s15
	v_add3_u32 v75, v77, v79, s15
	v_add3_u32 v76, v76, v80, s15
	v_add3_u32 v74, v74, v78, s15
	v_and_b32_e32 v75, 0xffff0000, v75
	v_and_b32_e32 v76, 0xffff0000, v76
	v_or_b32_sdwa v75, v75, v73 dst_sel:DWORD dst_unused:UNUSED_PAD src0_sel:DWORD src1_sel:WORD_1
	v_or_b32_sdwa v74, v76, v74 dst_sel:DWORD dst_unused:UNUSED_PAD src0_sel:DWORD src1_sel:WORD_1
	v_lshl_add_u64 v[76:77], v[140:141], 0, v[2:3]
	global_store_dwordx2 v[76:77], v[74:75], off
	s_branch .LBB0_120
